# grid barrier rewritten: per-XCD arrive, last WG of XCD writes back L2 and bumps top counter, all WGs poll the monotonic top counter directly (no division, one fewer signalling hop); stacked on v31
# speedup vs baseline: 1.0216x; 1.0063x over previous
.Lcvth_done2:
.LBB0_156:
	s_movk_i32 s32, 0x207
	s_mov_b32 s0, 0
	v_writelane_b32 v255, s0, 46
	s_add_u32 s0, s62, 0x22f28000
	s_addc_u32 s1, s63, 0
	v_writelane_b32 v251, s0, 37
	s_waitcnt vmcnt(11)
	v_mbcnt_lo_u32_b32 v0, -1, 0
	s_mov_b32 s89, 1
	v_writelane_b32 v251, s1, 38
	s_add_u32 s0, s62, 0x22f30000
	s_addc_u32 s1, s63, 0
	v_writelane_b32 v251, s0, 39
	s_waitcnt lgkmcnt(0)
	s_movk_i32 s33, 0x3000
	v_mov_b32_e32 v33, 0
	v_writelane_b32 v251, s1, 40
	s_add_u32 s0, s62, 0x1bee0000
	v_writelane_b32 v251, s0, 41
	s_addc_u32 s0, s63, 0
	v_writelane_b32 v251, s0, 42
	s_add_u32 s0, s62, 0x22f38200
	s_addc_u32 s1, s63, 0
	s_add_u32 s2, s62, 0x22f38400
	s_addc_u32 s3, s63, 0
	s_add_u32 s4, s62, 0x22f38500
	s_addc_u32 s5, s63, 0
	s_add_u32 s6, s62, 0x22f38600
	v_writelane_b32 v251, s0, 43
	s_addc_u32 s7, s63, 0
	v_mov_b32_e32 v228, 0x1000
	v_writelane_b32 v251, s1, 44
	s_add_u32 s0, s62, 0x22f38700
	s_addc_u32 s1, s63, 0
	v_writelane_b32 v251, s0, 45
	v_mov_b32_e32 v221, 0x2000
	v_mov_b32_e32 v248, 1
	v_writelane_b32 v251, s1, 46
	s_add_u32 s0, s62, 0x22f38800
	s_addc_u32 s1, s63, 0
	v_writelane_b32 v251, s0, 47
	v_mov_b32_e32 v224, 0x358637bd
	v_mbcnt_hi_u32_b32 v220, -1, v0
	v_writelane_b32 v251, s1, 48
	s_add_u32 s0, s62, 0x22f38900
	s_addc_u32 s1, s63, 0
	v_writelane_b32 v251, s0, 49
	v_mov_b32_e32 v225, 0x42800000
	v_not_b32_e32 v226, 63
	v_writelane_b32 v251, s1, 50
	s_add_u32 s0, s62, 0x22f38a00
	s_addc_u32 s1, s63, 0
	v_writelane_b32 v251, s0, 51
	v_mov_b32_e32 v227, 0x410000
	v_mov_b32_e32 v249, 0x160000
	v_writelane_b32 v251, s1, 52
	s_add_u32 s0, s62, 0x22f38b00
	s_addc_u32 s1, s63, 0
	v_writelane_b32 v251, s0, 53
	s_mov_b32 s94, 0x8200
	s_mov_b32 s66, 0xc2fc0000
	v_writelane_b32 v251, s1, 54
	s_add_u32 s0, s62, 0x22f38c00
	s_addc_u32 s1, s63, 0
	v_writelane_b32 v251, s0, 55
	s_movk_i32 s67, 0xffc0
	s_movk_i32 s88, 0x1000
	v_writelane_b32 v251, s1, 56
	s_add_u32 s0, s62, 0x22f38d00
	s_addc_u32 s1, s63, 0
	v_writelane_b32 v251, s0, 57
	s_mov_b32 s78, 0
	s_mov_b32 s97, 0
	v_writelane_b32 v251, s1, 58
	s_add_u32 s0, s62, 0x22f38e00
	s_addc_u32 s1, s63, 0
	v_writelane_b32 v251, s0, 59
	s_mov_b64 s[34:35], 0x100000
	s_mov_b64 s[68:69], 0x100800
	v_writelane_b32 v251, s1, 60
	s_add_u32 s0, s62, 0x22f38f00
	s_addc_u32 s1, s63, 0
	v_writelane_b32 v251, s0, 61
	s_mov_b64 s[84:85], 0x80
	s_nop 0
	v_writelane_b32 v251, s1, 62
	s_add_u32 s0, s62, 0x22f39000
	s_addc_u32 s1, s63, 0
	v_writelane_b32 v251, s0, 63
	s_nop 1
	v_writelane_b32 v252, s1, 0
	s_add_u32 s0, s62, 0x22f39100
	s_addc_u32 s1, s63, 0
	v_writelane_b32 v252, s0, 1
	s_nop 1
	v_writelane_b32 v252, s1, 2
	s_add_u32 s0, s62, 0x22f39200
	s_addc_u32 s1, s63, 0
	v_writelane_b32 v252, s0, 3
	s_nop 1
	v_writelane_b32 v252, s1, 4
	s_add_u32 s0, s62, 0x22f39300
	s_addc_u32 s1, s63, 0
	v_writelane_b32 v252, s0, 5
	s_nop 1
	v_writelane_b32 v252, s1, 6
	s_add_u32 s0, s62, 0x22f3b400
	s_addc_u32 s1, s63, 0
	s_add_u32 s52, s62, 0x22f3b500
	v_writelane_b32 v252, s0, 7
	s_addc_u32 s53, s63, 0
	s_nop 0
	v_writelane_b32 v252, s1, 8
	s_add_u32 s0, s62, 0x2080000
	s_addc_u32 s1, s63, 0
	v_writelane_b32 v252, s0, 9
	s_nop 1
	v_writelane_b32 v252, s1, 10
	s_add_u32 s0, s62, 0x22f3c000
	s_addc_u32 s1, s63, 0
	s_add_u32 s70, s62, 0x9a60000
	v_writelane_b32 v252, s0, 11
	s_addc_u32 s71, s63, 0
	s_nop 0
	v_writelane_b32 v252, s1, 12
	s_add_u32 s0, s62, 0x8200000
	s_addc_u32 s1, s63, 0
	v_writelane_b32 v252, s0, 13
	s_nop 1
	v_writelane_b32 v252, s1, 14
	s_add_u32 s0, s62, 0x15d60000
	s_addc_u32 s1, s63, 0
	s_add_u32 s92, s62, 0x4100000
	v_writelane_b32 v252, s0, 15
	s_addc_u32 s93, s63, 0
	s_nop 0
	v_writelane_b32 v252, s1, 16
	s_add_u32 s0, s62, 0x19e60000
	s_addc_u32 s1, s63, 0
	v_writelane_b32 v252, s0, 17
	s_nop 1
	v_writelane_b32 v252, s1, 18
	s_add_u32 s0, s62, 0x17de0000
	s_addc_u32 s1, s63, 0
	v_writelane_b32 v252, s0, 19
	s_bitcmp1_b32 s91, 0
	s_nop 0
	v_writelane_b32 v252, s1, 20
	s_cselect_b64 s[0:1], -1, 0
	v_writelane_b32 v252, s0, 21
	s_nop 1
	v_writelane_b32 v252, s1, 22
	s_add_u32 s0, s62, 0x23a3c000
	v_writelane_b32 v252, s0, 23
	s_addc_u32 s0, s63, 0
	v_writelane_b32 v252, s0, 24
	s_add_u32 s0, s62, 0x23abc000
	v_writelane_b32 v252, s0, 25
	v_writelane_b32 v252, s56, 26
	s_addc_u32 s0, s63, 0
	s_add_i32 s80, 0, 0x11000
	v_writelane_b32 v252, s57, 27
	v_writelane_b32 v252, s58, 28
	v_writelane_b32 v252, s59, 29
	v_writelane_b32 v252, s60, 30
	v_writelane_b32 v252, s61, 31
	v_writelane_b32 v252, s62, 32
	v_writelane_b32 v252, s63, 33
	v_writelane_b32 v252, s0, 34
	s_add_i32 s0, 0, 0x23ff0
	v_writelane_b32 v252, s0, 35
	s_add_i32 s0, 0, 0x23ff4
	v_writelane_b32 v252, s0, 36
	s_add_i32 s0, 0, 0x22000
	v_writelane_b32 v252, s0, 37
	v_writelane_b32 v252, s52, 38
	s_mov_b64 s[56:57], s[2:3]
	s_mov_b64 s[58:59], s[4:5]
	v_writelane_b32 v252, s53, 39
	v_writelane_b32 v252, s56, 40
	s_mov_b64 s[60:61], s[6:7]
	s_add_i32 s81, 0, 0x19800
	v_writelane_b32 v252, s57, 41
	v_writelane_b32 v252, s58, 42
	s_nop 1
	v_writelane_b32 v252, s59, 43
	v_writelane_b32 v252, s60, 44
	s_nop 1
	v_writelane_b32 v252, s61, 45
	v_writelane_b32 v252, s91, 46
	v_writelane_b32 v252, s54, 47
	s_nop 1
	v_writelane_b32 v252, s55, 48
	v_writelane_b32 v252, s64, 49
	s_nop 1
	v_writelane_b32 v252, s65, 50

.LBB0_179:
	s_waitcnt lgkmcnt(0)
	v_readfirstlane_b32 s2, v2
	v_readfirstlane_b32 s3, v0
	v_readlane_b32 s6, v255, 46
	s_lshl_b32 s0, s83, 8
	v_readlane_b32 s4, v251, 32
	v_readlane_b32 s5, v251, 33
	v_readlane_b32 s10, v252, 7
	v_readlane_b32 s11, v252, 8
	s_add_i32 s6, s6, 1
	s_add_u32 s0, s4, s0
	s_addc_u32 s1, s5, 0
	v_mov_b32_e32 v3, 0x1000
	v_mov_b32_e32 v4, 1
	v_mov_b32_e32 v5, 0
	v_writelane_b32 v255, s6, 46
	s_mul_i32 s7, s6, s2
	s_mul_i32 s8, s6, s3
	global_atomic_add v1, v3, v4, s[0:1] offset:1024 sc0
	s_mov_b32 s12, 0
	s_waitcnt vmcnt(0)
	v_readfirstlane_b32 s9, v1
	s_add_i32 s9, s9, 1
	s_cmp_lg_u32 s9, s7
	s_cbranch_scc1 .Lgb0_spin
	buffer_wbl2 sc1
	s_waitcnt vmcnt(0)
	global_atomic_add v5, v4, s[10:11]
.Lgb0_spin:
	global_load_dword v1, v5, s[10:11] sc1
	s_waitcnt vmcnt(0)
	v_readfirstlane_b32 s9, v1
	s_sub_i32 s9, s9, s8
	s_cmp_ge_i32 s9, 0
	s_cbranch_scc1 .Lgb0_done
	s_sleep 1
	s_add_i32 s12, s12, 1
	s_cmp_lt_u32 s12, 0x100000
	s_cbranch_scc1 .Lgb0_spin
.Lgb0_done:
	buffer_inv sc1
	s_waitcnt vmcnt(0)
.LBB0_215:
	s_or_b64 exec, exec, s[62:63]
	s_waitcnt lgkmcnt(0)
	s_barrier

.LBB0_268:
	s_waitcnt lgkmcnt(0)
	v_readfirstlane_b32 s2, v2
	v_readfirstlane_b32 s3, v0
	v_readlane_b32 s6, v255, 46
	s_lshl_b32 s0, s78, 8
	v_readlane_b32 s4, v251, 32
	v_readlane_b32 s5, v251, 33
	v_readlane_b32 s10, v252, 7
	v_readlane_b32 s11, v252, 8
	s_add_i32 s6, s6, 1
	s_add_u32 s0, s4, s0
	s_addc_u32 s1, s5, 0
	v_mov_b32_e32 v3, 0x1000
	v_mov_b32_e32 v4, 1
	v_mov_b32_e32 v5, 0
	v_writelane_b32 v255, s6, 46
	s_mul_i32 s7, s6, s2
	s_mul_i32 s8, s6, s3
	global_atomic_add v1, v3, v4, s[0:1] offset:1024 sc0
	s_mov_b32 s12, 0
	s_waitcnt vmcnt(0)
	v_readfirstlane_b32 s9, v1
	s_add_i32 s9, s9, 1
	s_cmp_lg_u32 s9, s7
	s_cbranch_scc1 .Lgb1_spin
	buffer_wbl2 sc1
	s_waitcnt vmcnt(0)
	global_atomic_add v5, v4, s[10:11]

.Lgb1_done:
	buffer_inv sc1
	s_waitcnt vmcnt(0)
.LBB0_304:
	s_or_b64 exec, exec, s[62:63]
	s_waitcnt lgkmcnt(0)
	s_barrier

.Lgb2_done:
	buffer_inv sc1
	s_waitcnt vmcnt(0)
.LBB0_375:
	s_or_b64 exec, exec, s[62:63]
	s_waitcnt lgkmcnt(0)
	s_barrier

.Lgb3_done:
	buffer_inv sc1
	s_waitcnt vmcnt(0)
.LBB0_510:
	s_or_b64 exec, exec, s[62:63]
	s_waitcnt lgkmcnt(0)
	s_barrier

.Lgb4_done:
	buffer_inv sc1
	s_waitcnt vmcnt(0)
.LBB0_591:
	s_or_b64 exec, exec, s[62:63]
	s_waitcnt lgkmcnt(0)
	s_barrier

.Lgb5_done:
	buffer_inv sc1
	s_waitcnt vmcnt(0)
.LBB0_656:
	s_or_b64 exec, exec, s[62:63]
	s_waitcnt lgkmcnt(0)
	s_barrier

.Lgb6_done:
	buffer_inv sc1
	s_waitcnt vmcnt(0)
.LBB0_853:
	s_or_b64 exec, exec, s[62:63]
	s_waitcnt lgkmcnt(0)
	s_barrier

.Lgb7_done:
	buffer_inv sc1
	s_waitcnt vmcnt(0)
.LBB0_1089:
	s_or_b64 exec, exec, s[62:63]
	s_waitcnt lgkmcnt(0)
	s_barrier

.Lgb8_done:
	buffer_inv sc1
	s_waitcnt vmcnt(0)
.LBB0_1180:
	s_or_b64 exec, exec, s[62:63]
	s_waitcnt lgkmcnt(0)
	s_barrier

.Lgb9_done:
	buffer_inv sc1
	s_waitcnt vmcnt(0)
.LBB0_1260:
	s_or_b64 exec, exec, s[72:73]
	s_waitcnt lgkmcnt(0)
	s_barrier

.Lgb10_done:
	buffer_inv sc1
	s_waitcnt vmcnt(0)
.LBB0_1337:
	s_or_b64 exec, exec, s[72:73]
	s_waitcnt lgkmcnt(0)
	s_barrier

.LBB0_1394:
	s_waitcnt lgkmcnt(0)
	v_readfirstlane_b32 s2, v2
	v_readfirstlane_b32 s3, v0
	v_readlane_b32 s6, v255, 46
	s_lshl_b32 s0, s33, 8
	v_readlane_b32 s4, v251, 32
	v_readlane_b32 s5, v251, 33
	v_readlane_b32 s10, v252, 7
	v_readlane_b32 s11, v252, 8
	s_add_i32 s6, s6, 1
	s_add_u32 s0, s4, s0
	s_addc_u32 s1, s5, 0
	v_mov_b32_e32 v3, 0x1000
	v_mov_b32_e32 v4, 1
	v_mov_b32_e32 v5, 0
	v_writelane_b32 v255, s6, 46
	s_mul_i32 s7, s6, s2
	s_mul_i32 s8, s6, s3
	global_atomic_add v1, v3, v4, s[0:1] offset:1024 sc0
	s_mov_b32 s12, 0
	s_waitcnt vmcnt(0)
	v_readfirstlane_b32 s9, v1
	s_add_i32 s9, s9, 1
	s_cmp_lg_u32 s9, s7
	s_cbranch_scc1 .Lgb11_spin
	buffer_wbl2 sc1
	s_waitcnt vmcnt(0)
	global_atomic_add v5, v4, s[10:11]

.Lgb11_done:
	buffer_inv sc1
	s_waitcnt vmcnt(0)
.LBB0_1430:
	s_or_b64 exec, exec, s[30:31]
	s_waitcnt lgkmcnt(0)
	s_barrier
